# conv-halo rows stored write-through in P1: no L2 write-back left in the P1|P2 seam for XCD-local teams (previously the 8 teams whose halo consumer sits on the next XCD wrote back their L2)
# speedup vs baseline: 1.0069x; 1.0059x over previous
; __device__ __forceinline__ u32x4 pack8(const f32x4 a, const f32x4 b) { u32x4 w; w.x = cvt_pk_bf16(a[0], a[1]); w.y = cvt_pk_bf16(a[2], a[3]); w.z = cvt_pk_bf16(b[0], b[1]); w.w = cvt_pk_bf16(b[2], b[3]); return w; }
;     __device__ __forceinline__ void operator()(const f32x4 (&acc)[2][2][4][2], const Unit& u, int wr, int wc, int fr, int fq) const {
;     ...
;                     const u32x4 w = pack8(v0, v1);
;                     *(u32x4*)(base + ((size_t)((r >> 6) * 4 + h)) * 32768 + part * 8192 + (r & 63) * 128 + c8) = w;
;                     if (grp == 1 && part < 3 && m == 3 && fr >= 13) *(u32x4*)(halo + (size_t)(r >> 6) * 4608 + (fr - 13) * 1536 + h * 384 + part * 128 + c8) = w;
.LBB0_168:
	s_cmp_gt_i32 s96, 7
	s_cselect_b64 s[16:17], -1, 0
	s_ashr_i32 s38, s49, 6
	s_and_b64 s[78:79], s[16:17], s[76:77]
	s_mul_i32 s76, s37, 0x180
	s_mul_hi_i32 s81, s38, 0x2400
	s_mul_i32 s80, s38, 0x2400
	v_lshlrev_b32_e32 v168, 1, v154
	v_mov_b32_e32 v169, v147
	s_ashr_i32 s77, s76, 31
	s_lshl_b32 s4, s4, 7
	v_cvt_pk_bf16_f32 v130, v130, v131
	v_cvt_pk_bf16_f32 v131, v132, v133
	v_cvt_pk_bf16_f32 v132, v134, v135
	v_cvt_pk_bf16_f32 v133, v136, v137
	v_lshl_add_u64 v[134:135], v[176:177], 0, v[168:169]
	s_and_b64 s[78:79], s[78:79], s[6:7]
	v_lshl_add_u64 v[176:177], v[156:157], 0, s[80:81]
	global_store_dwordx4 v[134:135], v[130:133], off
	s_and_saveexec_b64 s[80:81], s[78:79]
	s_cbranch_execz .LBB0_170
	v_lshl_add_u64 v[134:135], s[76:77], 1, v[176:177]
	s_lshl_b32 s38, s4, 1
	v_lshl_add_u64 v[134:135], v[134:135], 0, s[38:39]
	v_lshl_add_u64 v[134:135], v[134:135], 0, v[146:147]
	v_add_co_u32_e32 v134, vcc, 0xffff7000, v134
	s_nop 1
	v_addc_co_u32_e32 v135, vcc, -1, v135, vcc
	global_store_dwordx4 v[134:135], v[130:133], off offset:-3072 sc1

; __device__ __forceinline__ u32x4 pack8(const f32x4 a, const f32x4 b) { u32x4 w; w.x = cvt_pk_bf16(a[0], a[1]); w.y = cvt_pk_bf16(a[2], a[3]); w.z = cvt_pk_bf16(b[0], b[1]); w.w = cvt_pk_bf16(b[2], b[3]); return w; }
;     __device__ __forceinline__ void operator()(const f32x4 (&acc)[2][2][4][2], const Unit& u, int wr, int wc, int fr, int fq) const {
;     ...
;                     const u32x4 w = pack8(v0, v1);
;                     *(u32x4*)(base + ((size_t)((r >> 6) * 4 + h)) * 32768 + part * 8192 + (r & 63) * 128 + c8) = w;
;                     if (grp == 1 && part < 3 && m == 3 && fr >= 13) *(u32x4*)(halo + (size_t)(r >> 6) * 4608 + (fr - 13) * 1536 + h * 384 + part * 128 + c8) = w;
.LBB0_194:
	s_ashr_i32 s10, s38, 6
	v_mov_b32_e32 v169, v147
	s_mul_hi_i32 s11, s10, 0x2400
	s_mulk_i32 s10, 0x2400
	v_cvt_pk_bf16_f32 v130, v130, v131
	v_cvt_pk_bf16_f32 v131, v132, v133
	v_cvt_pk_bf16_f32 v132, v134, v135
	v_cvt_pk_bf16_f32 v133, v136, v137
	v_lshl_add_u64 v[134:135], v[180:181], 0, v[168:169]
	global_store_dwordx4 v[134:135], v[130:133], off
	v_lshl_add_u64 v[134:135], v[156:157], 0, s[10:11]
	s_and_saveexec_b64 s[10:11], s[78:79]
	s_cbranch_execz .LBB0_196
	v_lshl_add_u64 v[136:137], s[76:77], 1, v[134:135]
	s_lshl_b32 s38, s4, 1
	v_lshl_add_u64 v[136:137], v[136:137], 0, s[38:39]
	v_lshl_add_u64 v[136:137], v[136:137], 0, v[146:147]
	v_add_co_u32_e32 v136, vcc, 0xffff7000, v136
	s_nop 1
	v_addc_co_u32_e32 v137, vcc, -1, v137, vcc
	global_store_dwordx4 v[136:137], v[130:133], off offset:-3072 sc1

; __device__ __forceinline__ u32x4 pack8(const f32x4 a, const f32x4 b) { u32x4 w; w.x = cvt_pk_bf16(a[0], a[1]); w.y = cvt_pk_bf16(a[2], a[3]); w.z = cvt_pk_bf16(b[0], b[1]); w.w = cvt_pk_bf16(b[2], b[3]); return w; }
;     __device__ __forceinline__ void operator()(const f32x4 (&acc)[2][2][4][2], const Unit& u, int wr, int wc, int fr, int fq) const {
;     ...
;                     const u32x4 w = pack8(v0, v1);
;                     *(u32x4*)(base + ((size_t)((r >> 6) * 4 + h)) * 32768 + part * 8192 + (r & 63) * 128 + c8) = w;
;                     if (grp == 1 && part < 3 && m == 3 && fr >= 13) *(u32x4*)(halo + (size_t)(r >> 6) * 4608 + (fr - 13) * 1536 + h * 384 + part * 128 + c8) = w;
.LBB0_229:
	s_and_b64 s[14:15], s[16:17], s[70:71]
	s_mul_i32 s70, s51, 0x180
	v_mov_b32_e32 v169, v147
	s_ashr_i32 s71, s70, 31
	s_lshl_b32 s74, s74, 7
	v_cvt_pk_bf16_f32 v130, v130, v131
	v_cvt_pk_bf16_f32 v131, v180, v181
	v_cvt_pk_bf16_f32 v132, v132, v133
	v_cvt_pk_bf16_f32 v133, v182, v183
	v_lshl_add_u64 v[178:179], v[178:179], 0, v[168:169]
	s_and_b64 s[72:73], s[14:15], s[6:7]
	global_store_dwordx4 v[178:179], v[130:133], off
	s_and_saveexec_b64 s[14:15], s[72:73]
	s_cbranch_execz .LBB0_231
	v_lshl_add_u64 v[176:177], s[70:71], 1, v[176:177]
	s_lshl_b32 s38, s74, 1
	v_lshl_add_u64 v[176:177], v[176:177], 0, s[38:39]
	v_lshl_add_u64 v[176:177], v[176:177], 0, v[146:147]
	v_add_co_u32_e32 v176, vcc, 0xffff7000, v176
	s_nop 1
	v_addc_co_u32_e32 v177, vcc, -1, v177, vcc
	global_store_dwordx4 v[176:177], v[130:133], off offset:-3072 sc1

; __device__ __forceinline__ u32x4 pack8(const f32x4 a, const f32x4 b) { u32x4 w; w.x = cvt_pk_bf16(a[0], a[1]); w.y = cvt_pk_bf16(a[2], a[3]); w.z = cvt_pk_bf16(b[0], b[1]); w.w = cvt_pk_bf16(b[2], b[3]); return w; }
;     __device__ __forceinline__ void operator()(const f32x4 (&acc)[2][2][4][2], const Unit& u, int wr, int wc, int fr, int fq) const {
;     ...
;                     const u32x4 w = pack8(v0, v1);
;                     *(u32x4*)(base + ((size_t)((r >> 6) * 4 + h)) * 32768 + part * 8192 + (r & 63) * 128 + c8) = w;
;                     if (grp == 1 && part < 3 && m == 3 && fr >= 13) *(u32x4*)(halo + (size_t)(r >> 6) * 4608 + (fr - 13) * 1536 + h * 384 + part * 128 + c8) = w;
.LBB0_255:
	v_mov_b32_e32 v169, v147
	v_cvt_pk_bf16_f32 v130, v130, v131
	v_cvt_pk_bf16_f32 v131, v170, v171
	v_cvt_pk_bf16_f32 v132, v132, v133
	v_cvt_pk_bf16_f32 v133, v172, v173
	v_lshl_add_u64 v[136:137], v[136:137], 0, v[168:169]
	global_store_dwordx4 v[136:137], v[130:133], off
	s_and_saveexec_b64 s[10:11], s[72:73]
	s_cbranch_execz .LBB0_257
	v_lshl_add_u64 v[134:135], s[70:71], 1, v[134:135]
	s_lshl_b32 s38, s74, 1
	v_lshl_add_u64 v[134:135], v[134:135], 0, s[38:39]
	v_lshl_add_u64 v[134:135], v[134:135], 0, v[146:147]
	v_add_co_u32_e32 v134, vcc, 0xffff7000, v134
	s_nop 1
	v_addc_co_u32_e32 v135, vcc, -1, v135, vcc
	global_store_dwordx4 v[134:135], v[130:133], off offset:-3072 sc1

; __device__ __forceinline__ unsigned xb_ld(unsigned* p)              { return __hip_atomic_load(p, __ATOMIC_RELAXED, __HIP_MEMORY_SCOPE_AGENT); }
; __device__ __forceinline__ unsigned xb_add(unsigned* p, unsigned v) { return __hip_atomic_fetch_add(p, v, __ATOMIC_RELAXED, __HIP_MEMORY_SCOPE_AGENT); }
; #define XB_SPIN(cond, bar) do { unsigned _sp = 0; while (cond) { __builtin_amdgcn_s_sleep(1); \
;     if ((++_sp & 255u) == 0u) { if (xb_ld(&(bar)[XB_TMO])) break; if (_sp > XB_SPIN_CAP) { atomicAdd(&(bar)[XB_TMO], 1u); break; } } } } while (0)
; __device__ __forceinline__ void team_barrier(unsigned* ctr, unsigned target, unsigned* bar) {
;     asm volatile("s_waitcnt vmcnt(0)" ::: "memory");
;     __syncthreads();
;     if (threadIdx.x == 0) {
;         __builtin_amdgcn_s_waitcnt(0);
;         (void)xb_add(ctr, 1u);
;         asm volatile("buffer_inv sc1" ::: "memory");
;         XB_SPIN(xb_ld(ctr) < target, bar);
;         asm volatile("s_waitcnt vmcnt(0)" ::: "memory");
;     }
;     __syncthreads();
; }
.Lts1_a:
	s_or_b64 exec, exec, s[6:7]
	s_waitcnt vmcnt(0)
	s_barrier
	s_and_saveexec_b64 s[6:7], s[96:97]
	s_cbranch_execz .Lts1_join
	s_add_i32 s3, s90, 1
	v_xor_b32_e32 v2, s3, v2
	v_xor_b32_e32 v3, s3, v3
	v_xor_b32_e32 v4, s3, v4
	v_xor_b32_e32 v5, s3, v5
	v_xor_b32_e32 v6, s3, v6
	v_xor_b32_e32 v7, s3, v7
	v_xor_b32_e32 v8, s3, v8
	v_xor_b32_e32 v9, s3, v9
	v_or3_b32 v2, v2, v3, v4
	v_or_b32_e32 v2, v2, v5
	v_cmp_ne_u32_e32 vcc, 0, v2
	s_cbranch_vccz .Lts1_nowb
	buffer_wbl2 sc1
	s_waitcnt vmcnt(0)
